# pass-2 importance atomics no longer followed by lgkmcnt(0) waits (LDS ops are in order, atomics return nothing); x+0 adds removed; on top of readlane descriptors and ds_add_f32
# speedup vs baseline: 1.0028x; 1.0028x over previous
; template <int MODE>
; __device__ __forceinline__ void step_fragb(const bf16x8 (&qf)[4], bf16x8 (&kf)[2][4], FragV& cur, const bf16_t* __restrict__ KF, const bf16_t* __restrict__ VF,
;                                            int pos0, int pnext, int lo, int hi, AState& st, int lane, LAS float* imp) {
;     ...
;     } else {
;         if (__builtin_amdgcn_ballot_w64(mx > st.m + 40.f) != 0ull) {
;             mx = fmaxf(mx, __shfl_xor(mx, 16)); mx = fmaxf(mx, __shfl_xor(mx, 32));
;             const float mn = fmaxf(st.m, mx), alpha = __builtin_amdgcn_exp2f(st.m - mn); st.m = mn; st.l *= alpha;
;             if (MODE == 0) {
; #pragma unroll
;                 for (int j = 0; j < 8; ++j) st.o[j] = st.o[j] * alpha;
;             }
;         }
;         float ps = 0.f;
; #pragma unroll
;         for (int j = 0; j < 8; ++j) { p[j] = vd[j] ? __builtin_amdgcn_exp2f(sc[j] - st.m) : 0.f; ps += p[j]; }
;         st.l += ps;
.LBB0_831:
	v_sub_f32_e32 v53, v53, v143
	v_exp_f32_e32 v53, v53
	v_sub_f32_e32 v54, v54, v143
	v_exp_f32_e32 v54, v54
	v_sub_f32_e32 v55, v55, v143
	v_exp_f32_e32 v55, v55
	v_sub_f32_e32 v56, v56, v143
	v_exp_f32_e32 v56, v56
	v_cndmask_b32_e64 v54, 0, v54, s[14:15]
	v_cndmask_b32_e64 v53, 0, v53, s[10:11]
	v_add_f32_e32 v53, v54, v53
	v_cndmask_b32_e64 v54, 0, v55, s[12:13]
	v_sub_f32_e32 v55, v57, v143
	v_add_f32_e32 v53, v54, v53
	v_cndmask_b32_e64 v54, 0, v56, s[18:19]
	v_exp_f32_e32 v55, v55
	v_sub_f32_e32 v56, v58, v143
	v_exp_f32_e32 v56, v56
	v_add_f32_e32 v53, v54, v53
	v_cndmask_b32_e64 v54, 0, v55, s[16:17]
	v_sub_f32_e32 v55, v59, v143
	v_add_f32_e32 v53, v54, v53
	v_cndmask_b32_e64 v54, 0, v56, s[20:21]
	v_exp_f32_e32 v55, v55
	v_sub_f32_e32 v56, v60, v143
	v_exp_f32_e32 v56, v56
	v_add_f32_e32 v53, v54, v53
	v_cndmask_b32_e64 v54, 0, v55, s[22:23]
	v_add_f32_e32 v53, v54, v53
	v_cndmask_b32_e64 v54, 0, v56, s[24:25]
	v_add_f32_e32 v53, v54, v53
	s_cmp_lg_u32 s42, s66
	v_add_f32_e32 v52, v52, v53
	s_cbranch_scc0 .LBB0_835

; template <bool SLC, bool NOMASK> ...
;     ...
;     f32x4 pa, pb; float ps = 0.f;
;     const float mref = st.m - 4.f;
;     if (NOMASK) {
; #pragma unroll
;         for (int j = 0; j < 4; ++j) { pa[j] = __builtin_amdgcn_exp2f(sc[j] - mref); pb[j] = __builtin_amdgcn_exp2f(sc[4 + j] - mref); }
;         if (SLC) {
; #pragma unroll
;             for (int j = 0; j < 4; ++j) { pa[j] = act ? pa[j] : 0.f; pb[j] = act ? pb[j] : 0.f; }
;         }
; #pragma unroll
;         for (int j = 0; j < 4; ++j) ps += pa[j] + pb[j];
;     } else {
; #pragma unroll
;         for (int j = 0; j < 4; ++j) { pa[j] = vd[j] ? __builtin_amdgcn_exp2f(sc[j] - mref) : 0.f; pb[j] = vd[4 + j] ? __builtin_amdgcn_exp2f(sc[4 + j] - mref) : 0.f; ps += pa[j] + pb[j]; }
;     }
;     st.l += ps;
;     const u32x2 pw = pack8_fp8(pa, pb);
;     const i64_t pf = __builtin_bit_cast(i64_t, pw);
; #pragma unroll
;     for (int db = 0; db < 8; ++db) st.o[db] = __builtin_amdgcn_mfma_f32_16x16x32_fp8_fp8(cur.v[db], pf, st.o[db], 0, 0, 0);
.LBB0_869:
	v_add_f32_e32 v34, -4.0, v0
	v_sub_f32_e32 v2, v2, v34
	v_sub_f32_e32 v6, v6, v34
	v_sub_f32_e32 v3, v3, v34
	v_sub_f32_e32 v7, v7, v34
	v_exp_f32_e32 v2, v2
	v_exp_f32_e32 v6, v6
	v_exp_f32_e32 v3, v3
	v_exp_f32_e32 v7, v7
	v_sub_f32_e32 v4, v4, v34
	v_sub_f32_e32 v8, v8, v34
	v_sub_f32_e32 v5, v5, v34
	v_sub_f32_e32 v9, v9, v34
	v_exp_f32_e32 v4, v4
	v_exp_f32_e32 v8, v8
	v_exp_f32_e32 v5, v5
	v_exp_f32_e32 v9, v9
	v_cndmask_b32_e64 v34, 0, v2, s[10:11]
	v_cndmask_b32_e64 v6, 0, v6, s[10:11]
	v_cndmask_b32_e64 v35, 0, v3, s[10:11]
	v_cndmask_b32_e64 v7, 0, v7, s[10:11]
	v_mov_b32_e32 v2, v1
	v_mov_b32_e32 v3, v1
	v_cvt_pk_fp8_f32 v2, v34, v35
	v_cvt_pk_fp8_f32 v3, v6, v7
	v_cndmask_b32_e64 v4, 0, v4, s[10:11]
	v_cndmask_b32_e64 v205, 0, v8, s[10:11]
	v_cndmask_b32_e64 v5, 0, v5, s[10:11]
	v_cndmask_b32_e64 v229, 0, v9, s[10:11]
	v_add_f32_e32 v6, v34, v6
	v_cvt_pk_fp8_f32 v2, v4, v5 op_sel:[0,0,1]
	v_cvt_pk_fp8_f32 v3, v205, v229 op_sel:[0,0,1]
	v_add_f32_e32 v7, v35, v7
	v_add_f32_e32 v6, v7, v6
	v_add_f32_e32 v4, v4, v205
	v_add_f32_e32 v4, v4, v6
	v_add_f32_e32 v5, v5, v229
	v_add_f32_e32 v4, v5, v4
	s_waitcnt vmcnt(19)
	v_mfma_f32_16x16x32_fp8_fp8 v[8:11], v[90:91], v[2:3], v[64:67]
	v_add_f32_e32 v133, v133, v4
	v_mfma_f32_16x16x32_fp8_fp8 v[12:15], v[92:93], v[2:3], v[60:63]
	s_waitcnt vmcnt(18)
	v_mfma_f32_16x16x32_fp8_fp8 v[16:19], v[94:95], v[2:3], v[56:59]
	v_mfma_f32_16x16x32_fp8_fp8 v[20:23], v[96:97], v[2:3], v[52:55]
	s_waitcnt vmcnt(17)
	v_mfma_f32_16x16x32_fp8_fp8 v[24:27], v[98:99], v[2:3], v[48:51]
	v_mfma_f32_16x16x32_fp8_fp8 v[32:35], v[100:101], v[2:3], v[44:47]
	s_waitcnt vmcnt(16)
	v_mfma_f32_16x16x32_fp8_fp8 v[28:31], v[102:103], v[2:3], v[40:43]
	v_mfma_f32_16x16x32_fp8_fp8 v[4:7], v[104:105], v[2:3], v[36:39]
	s_nop 1
	s_branch .LBB0_863

; template <bool SLC, bool NOMASK> ...
;     ...
;     } else {
; #pragma unroll
;         for (int j = 0; j < 4; ++j) { pa[j] = vd[j] ? __builtin_amdgcn_exp2f(sc[j] - mref) : 0.f; pb[j] = vd[4 + j] ? __builtin_amdgcn_exp2f(sc[4 + j] - mref) : 0.f; ps += pa[j] + pb[j]; }
;     }
;     st.l += ps;
;     const u32x2 pw = pack8_fp8(pa, pb);
;     const i64_t pf = __builtin_bit_cast(i64_t, pw);
; #pragma unroll
;     for (int db = 0; db < 8; ++db) st.o[db] = __builtin_amdgcn_mfma_f32_16x16x32_fp8_fp8(cur.v[db], pf, st.o[db], 0, 0, 0);
.LBB0_872:
	v_add_f32_e32 v0, -4.0, v202
	v_sub_f32_e32 v2, v2, v0
	v_exp_f32_e32 v2, v2
	v_sub_f32_e32 v6, v6, v0
	v_exp_f32_e32 v6, v6
	v_sub_f32_e32 v4, v4, v0
	v_cndmask_b32_e64 v28, 0, v2, s[16:17]
	v_sub_f32_e32 v2, v3, v0
	v_exp_f32_e32 v2, v2
	v_sub_f32_e32 v3, v7, v0
	v_exp_f32_e32 v3, v3
	v_sub_f32_e32 v7, v8, v0
	v_cndmask_b32_e64 v29, 0, v2, s[12:13]
	v_sub_f32_e32 v2, v5, v0
	v_sub_f32_e32 v0, v9, v0
	v_cndmask_b32_e64 v6, 0, v6, s[24:25]
	v_exp_f32_e32 v4, v4
	v_exp_f32_e32 v7, v7
	v_cndmask_b32_e64 v30, 0, v3, s[20:21]
	v_exp_f32_e32 v5, v2
	v_exp_f32_e32 v0, v0
	v_mov_b32_e32 v2, v1
	v_mov_b32_e32 v3, v1
	v_cvt_pk_fp8_f32 v2, v28, v29
	v_cvt_pk_fp8_f32 v3, v6, v30
	v_cndmask_b32_e64 v4, 0, v4, s[14:15]
	v_cndmask_b32_e64 v7, 0, v7, s[22:23]
	v_cndmask_b32_e64 v5, 0, v5, s[10:11]
	v_cndmask_b32_e64 v0, 0, v0, s[18:19]
	v_cvt_pk_fp8_f32 v2, v4, v5 op_sel:[0,0,1]
	v_cvt_pk_fp8_f32 v3, v7, v0 op_sel:[0,0,1]
	v_add_f32_e32 v6, v28, v6
	v_add_f32_e32 v28, v29, v30
	v_add_f32_e32 v6, v28, v6
	v_add_f32_e32 v4, v4, v7
	v_add_f32_e32 v4, v4, v6
	v_add_f32_e32 v0, v5, v0
	s_waitcnt vmcnt(19)
	v_mfma_f32_16x16x32_fp8_fp8 v[8:11], v[90:91], v[2:3], v[64:67]
	v_add_f32_e32 v0, v0, v4
	v_add_f32_e32 v133, v203, v0
	v_mov_b32_e32 v0, v202
	v_mfma_f32_16x16x32_fp8_fp8 v[12:15], v[92:93], v[2:3], v[60:63]
	s_waitcnt vmcnt(18)
	v_mfma_f32_16x16x32_fp8_fp8 v[16:19], v[94:95], v[2:3], v[56:59]
	v_mfma_f32_16x16x32_fp8_fp8 v[20:23], v[96:97], v[2:3], v[52:55]
	s_waitcnt vmcnt(17)
	v_mfma_f32_16x16x32_fp8_fp8 v[24:27], v[98:99], v[2:3], v[48:51]
	v_mfma_f32_16x16x32_fp8_fp8 v[32:35], v[100:101], v[2:3], v[44:47]
	s_waitcnt vmcnt(16)
	v_mfma_f32_16x16x32_fp8_fp8 v[28:31], v[102:103], v[2:3], v[40:43]
	v_mfma_f32_16x16x32_fp8_fp8 v[4:7], v[104:105], v[2:3], v[36:39]
	s_nop 1
	s_add_i32 s10, s58, -3
	s_cmp_ge_u32 s10, s56
	s_mov_b64 s[10:11], -1
	s_cbranch_scc0 .LBB0_864

; template <bool SLC, bool NOMASK> ...
;     ...
;     } else {
; #pragma unroll
;         for (int j = 0; j < 4; ++j) { pa[j] = vd[j] ? __builtin_amdgcn_exp2f(sc[j] - mref) : 0.f; pb[j] = vd[4 + j] ? __builtin_amdgcn_exp2f(sc[4 + j] - mref) : 0.f; ps += pa[j] + pb[j]; }
;     }
;     st.l += ps;
;     const u32x2 pw = pack8_fp8(pa, pb);
;     const i64_t pf = __builtin_bit_cast(i64_t, pw);
; #pragma unroll
;     for (int db = 0; db < 8; ++db) st.o[db] = __builtin_amdgcn_mfma_f32_16x16x32_fp8_fp8(cur.v[db], pf, st.o[db], 0, 0, 0);
.LBB0_879:
	v_add_f32_e32 v2, -4.0, v0
	v_sub_f32_e32 v3, v36, v2
	v_exp_f32_e32 v3, v3
	v_sub_f32_e32 v36, v40, v2
	v_exp_f32_e32 v36, v36
	v_mov_b32_e32 v203, v0
	v_cndmask_b32_e64 v56, 0, v3, s[16:17]
	v_sub_f32_e32 v3, v37, v2
	v_cndmask_b32_e64 v57, 0, v36, s[24:25]
	v_exp_f32_e32 v3, v3
	v_sub_f32_e32 v36, v41, v2
	v_sub_f32_e32 v37, v38, v2
	v_exp_f32_e32 v36, v36
	v_exp_f32_e32 v37, v37
	v_sub_f32_e32 v38, v42, v2
	v_cndmask_b32_e64 v58, 0, v3, s[12:13]
	v_sub_f32_e32 v3, v39, v2
	v_sub_f32_e32 v2, v43, v2
	v_exp_f32_e32 v38, v38
	v_cndmask_b32_e64 v59, 0, v36, s[20:21]
	v_cndmask_b32_e64 v60, 0, v37, s[14:15]
	v_exp_f32_e32 v36, v3
	v_exp_f32_e32 v37, v2
	v_mov_b32_e32 v2, v1
	v_mov_b32_e32 v3, v1
	v_cvt_pk_fp8_f32 v2, v56, v58
	v_cvt_pk_fp8_f32 v3, v57, v59
	v_cndmask_b32_e64 v61, 0, v38, s[22:23]
	v_cndmask_b32_e64 v64, 0, v36, s[10:11]
	v_cndmask_b32_e64 v65, 0, v37, s[18:19]
	v_cvt_pk_fp8_f32 v2, v60, v64 op_sel:[0,0,1]
	v_cvt_pk_fp8_f32 v3, v61, v65 op_sel:[0,0,1]
	s_nop 0
	s_waitcnt vmcnt(19)
	v_mfma_f32_16x16x32_fp8_fp8 v[36:39], v[106:107], v[2:3], v[8:11]
	s_nop 2
	v_add_f32_e32 v8, v56, v57
	v_add_f32_e32 v9, v58, v59
	v_add_f32_e32 v8, v9, v8
	v_add_f32_e32 v9, v60, v61
	v_mfma_f32_16x16x32_fp8_fp8 v[40:43], v[108:109], v[2:3], v[12:15]
	v_add_f32_e32 v8, v9, v8
	v_add_f32_e32 v9, v64, v65
	v_add_f32_e32 v8, v9, v8
	s_waitcnt vmcnt(18)
	v_mfma_f32_16x16x32_fp8_fp8 v[44:47], v[110:111], v[2:3], v[16:19]
	v_add_f32_e32 v204, v133, v8
	v_mfma_f32_16x16x32_fp8_fp8 v[48:51], v[112:113], v[2:3], v[20:23]
	s_waitcnt vmcnt(17)
	v_mfma_f32_16x16x32_fp8_fp8 v[52:55], v[114:115], v[2:3], v[24:27]
	v_mfma_f32_16x16x32_fp8_fp8 v[56:59], v[116:117], v[2:3], v[32:35]
	s_waitcnt vmcnt(16)
	v_mfma_f32_16x16x32_fp8_fp8 v[60:63], v[134:135], v[2:3], v[28:31]
	v_mfma_f32_16x16x32_fp8_fp8 v[64:67], v[136:137], v[2:3], v[4:7]
	s_nop 1
	s_andn2_b64 vcc, exec, s[26:27]
	s_mov_b64 s[10:11], -1
	s_cbranch_vccnz .LBB0_859

; template <bool SLC, bool NOMASK> ...
;     ...
;     f32x4 pa, pb; float ps = 0.f;
;     const float mref = st.m - 4.f;
;     if (NOMASK) {
; #pragma unroll
;         for (int j = 0; j < 4; ++j) { pa[j] = __builtin_amdgcn_exp2f(sc[j] - mref); pb[j] = __builtin_amdgcn_exp2f(sc[4 + j] - mref); }
;         if (SLC) {
; #pragma unroll
;             for (int j = 0; j < 4; ++j) { pa[j] = act ? pa[j] : 0.f; pb[j] = act ? pb[j] : 0.f; }
;         }
; #pragma unroll
;         for (int j = 0; j < 4; ++j) ps += pa[j] + pb[j];
;     } else {
; #pragma unroll
;         for (int j = 0; j < 4; ++j) { pa[j] = vd[j] ? __builtin_amdgcn_exp2f(sc[j] - mref) : 0.f; pb[j] = vd[4 + j] ? __builtin_amdgcn_exp2f(sc[4 + j] - mref) : 0.f; ps += pa[j] + pb[j]; }
;     }
;     st.l += ps;
;     const u32x2 pw = pack8_fp8(pa, pb);
;     const i64_t pf = __builtin_bit_cast(i64_t, pw);
; #pragma unroll
;     for (int db = 0; db < 8; ++db) st.o[db] = __builtin_amdgcn_mfma_f32_16x16x32_fp8_fp8(cur.v[db], pf, st.o[db], 0, 0, 0);
.LBB0_883:
	v_add_f32_e32 v34, -4.0, v202
	v_sub_f32_e32 v2, v2, v34
	v_sub_f32_e32 v6, v6, v34
	v_sub_f32_e32 v3, v3, v34
	v_sub_f32_e32 v7, v7, v34
	v_exp_f32_e32 v2, v2
	v_exp_f32_e32 v6, v6
	v_exp_f32_e32 v3, v3
	v_exp_f32_e32 v7, v7
	v_sub_f32_e32 v4, v4, v34
	v_sub_f32_e32 v8, v8, v34
	v_sub_f32_e32 v5, v5, v34
	v_sub_f32_e32 v9, v9, v34
	v_exp_f32_e32 v4, v4
	v_exp_f32_e32 v8, v8
	v_exp_f32_e32 v5, v5
	v_exp_f32_e32 v9, v9
	v_cndmask_b32_e64 v34, 0, v2, s[10:11]
	v_cndmask_b32_e64 v6, 0, v6, s[10:11]
	v_cndmask_b32_e64 v35, 0, v3, s[10:11]
	v_cndmask_b32_e64 v7, 0, v7, s[10:11]
	v_mov_b32_e32 v2, v1
	v_mov_b32_e32 v3, v1
	v_cvt_pk_fp8_f32 v2, v34, v35
	v_cvt_pk_fp8_f32 v3, v6, v7
	v_cndmask_b32_e64 v4, 0, v4, s[10:11]
	v_cndmask_b32_e64 v205, 0, v8, s[10:11]
	v_cndmask_b32_e64 v5, 0, v5, s[10:11]
	v_cndmask_b32_e64 v229, 0, v9, s[10:11]
	v_add_f32_e32 v6, v34, v6
	v_cvt_pk_fp8_f32 v2, v4, v5 op_sel:[0,0,1]
	v_cvt_pk_fp8_f32 v3, v205, v229 op_sel:[0,0,1]
	v_add_f32_e32 v7, v35, v7
	v_add_f32_e32 v6, v7, v6
	v_add_f32_e32 v4, v4, v205
	v_add_f32_e32 v4, v4, v6
	v_add_f32_e32 v5, v5, v229
	v_add_f32_e32 v4, v5, v4
	s_waitcnt vmcnt(19)
	v_mfma_f32_16x16x32_fp8_fp8 v[8:11], v[170:171], v[2:3], v[36:39]
	v_add_f32_e32 v133, v133, v4
	s_mov_b64 s[10:11], 0
	v_mfma_f32_16x16x32_fp8_fp8 v[12:15], v[172:173], v[2:3], v[40:43]
	s_waitcnt vmcnt(18)
	v_mfma_f32_16x16x32_fp8_fp8 v[16:19], v[174:175], v[2:3], v[44:47]
	v_mfma_f32_16x16x32_fp8_fp8 v[20:23], v[176:177], v[2:3], v[48:51]
	s_waitcnt vmcnt(17)
	v_mfma_f32_16x16x32_fp8_fp8 v[24:27], v[178:179], v[2:3], v[52:55]
	v_mfma_f32_16x16x32_fp8_fp8 v[32:35], v[180:181], v[2:3], v[56:59]
	s_waitcnt vmcnt(16)
	v_mfma_f32_16x16x32_fp8_fp8 v[28:31], v[182:183], v[2:3], v[60:63]
	v_mfma_f32_16x16x32_fp8_fp8 v[4:7], v[184:185], v[2:3], v[64:67]
	s_nop 1

; template <bool SLC, bool NOMASK> ...
;     ...
;     } else {
; #pragma unroll
;         for (int j = 0; j < 4; ++j) { pa[j] = vd[j] ? __builtin_amdgcn_exp2f(sc[j] - mref) : 0.f; pb[j] = vd[4 + j] ? __builtin_amdgcn_exp2f(sc[4 + j] - mref) : 0.f; ps += pa[j] + pb[j]; }
;     }
;     st.l += ps;
;     const u32x2 pw = pack8_fp8(pa, pb);
;     const i64_t pf = __builtin_bit_cast(i64_t, pw);
; #pragma unroll
;     for (int db = 0; db < 8; ++db) st.o[db] = __builtin_amdgcn_mfma_f32_16x16x32_fp8_fp8(cur.v[db], pf, st.o[db], 0, 0, 0);
.LBB0_887:
	v_add_f32_e32 v0, -4.0, v203
	v_sub_f32_e32 v2, v2, v0
	v_exp_f32_e32 v2, v2
	v_sub_f32_e32 v6, v6, v0
	v_exp_f32_e32 v6, v6
	v_sub_f32_e32 v4, v4, v0
	v_cndmask_b32_e64 v28, 0, v2, s[16:17]
	v_sub_f32_e32 v2, v3, v0
	v_exp_f32_e32 v2, v2
	v_sub_f32_e32 v3, v7, v0
	v_exp_f32_e32 v3, v3
	v_sub_f32_e32 v7, v8, v0
	v_cndmask_b32_e64 v29, 0, v2, s[12:13]
	v_sub_f32_e32 v2, v5, v0
	v_sub_f32_e32 v0, v9, v0
	v_cndmask_b32_e64 v6, 0, v6, s[24:25]
	v_exp_f32_e32 v4, v4
	v_exp_f32_e32 v7, v7
	v_cndmask_b32_e64 v30, 0, v3, s[20:21]
	v_exp_f32_e32 v5, v2
	v_exp_f32_e32 v0, v0
	v_mov_b32_e32 v2, v1
	v_mov_b32_e32 v3, v1
	v_cvt_pk_fp8_f32 v2, v28, v29
	v_cvt_pk_fp8_f32 v3, v6, v30
	v_cndmask_b32_e64 v4, 0, v4, s[14:15]
	v_cndmask_b32_e64 v7, 0, v7, s[22:23]
	v_cndmask_b32_e64 v5, 0, v5, s[10:11]
	v_cndmask_b32_e64 v0, 0, v0, s[18:19]
	v_cvt_pk_fp8_f32 v2, v4, v5 op_sel:[0,0,1]
	v_cvt_pk_fp8_f32 v3, v7, v0 op_sel:[0,0,1]
	v_add_f32_e32 v6, v28, v6
	v_add_f32_e32 v28, v29, v30
	v_add_f32_e32 v6, v28, v6
	v_add_f32_e32 v4, v4, v7
	v_add_f32_e32 v4, v4, v6
	v_add_f32_e32 v0, v5, v0
	s_waitcnt vmcnt(19)
	v_mfma_f32_16x16x32_fp8_fp8 v[8:11], v[170:171], v[2:3], v[36:39]
	v_add_f32_e32 v0, v0, v4
	v_add_f32_e32 v133, v204, v0
	v_mov_b32_e32 v202, v203
	v_mfma_f32_16x16x32_fp8_fp8 v[12:15], v[172:173], v[2:3], v[40:43]
	s_waitcnt vmcnt(18)
	v_mfma_f32_16x16x32_fp8_fp8 v[16:19], v[174:175], v[2:3], v[44:47]
	v_mfma_f32_16x16x32_fp8_fp8 v[20:23], v[176:177], v[2:3], v[48:51]
	s_waitcnt vmcnt(17)
	v_mfma_f32_16x16x32_fp8_fp8 v[24:27], v[178:179], v[2:3], v[52:55]
	v_mfma_f32_16x16x32_fp8_fp8 v[32:35], v[180:181], v[2:3], v[56:59]
	s_waitcnt vmcnt(16)
	v_mfma_f32_16x16x32_fp8_fp8 v[28:31], v[182:183], v[2:3], v[60:63]
	v_mfma_f32_16x16x32_fp8_fp8 v[4:7], v[184:185], v[2:3], v[64:67]
	s_nop 1

; template <bool SLC, bool NOMASK> ...
;     ...
;     } else {
; #pragma unroll
;         for (int j = 0; j < 4; ++j) { pa[j] = vd[j] ? __builtin_amdgcn_exp2f(sc[j] - mref) : 0.f; pb[j] = vd[4 + j] ? __builtin_amdgcn_exp2f(sc[4 + j] - mref) : 0.f; ps += pa[j] + pb[j]; }
;     }
;     st.l += ps;
;     const u32x2 pw = pack8_fp8(pa, pb);
;     const i64_t pf = __builtin_bit_cast(i64_t, pw);
; #pragma unroll
;     for (int db = 0; db < 8; ++db) st.o[db] = __builtin_amdgcn_mfma_f32_16x16x32_fp8_fp8(cur.v[db], pf, st.o[db], 0, 0, 0);
.LBB0_912:
	v_add_f32_e32 v0, -4.0, v229
	v_sub_f32_e32 v36, v36, v0
	v_exp_f32_e32 v36, v36
	v_sub_f32_e32 v40, v40, v0
	v_exp_f32_e32 v40, v40
	v_sub_f32_e32 v38, v38, v0
	v_cndmask_b32_e64 v56, 0, v36, s[16:17]
	v_sub_f32_e32 v36, v37, v0
	v_exp_f32_e32 v36, v36
	v_sub_f32_e32 v37, v41, v0
	v_exp_f32_e32 v37, v37
	v_cndmask_b32_e64 v57, 0, v40, s[24:25]
	v_sub_f32_e32 v40, v42, v0
	v_cndmask_b32_e64 v58, 0, v36, s[12:13]
	v_sub_f32_e32 v36, v39, v0
	v_sub_f32_e32 v0, v43, v0
	v_exp_f32_e32 v38, v38
	v_exp_f32_e32 v40, v40
	v_cndmask_b32_e64 v59, 0, v37, s[20:21]
	v_exp_f32_e32 v36, v36
	v_exp_f32_e32 v0, v0
	v_mov_b32_e32 v64, v1
	v_mov_b32_e32 v65, v1
	v_cvt_pk_fp8_f32 v64, v56, v58
	v_cvt_pk_fp8_f32 v65, v57, v59
	v_cndmask_b32_e64 v60, 0, v38, s[14:15]
	v_cndmask_b32_e64 v61, 0, v40, s[22:23]
	v_cndmask_b32_e64 v66, 0, v36, s[10:11]
	v_cndmask_b32_e64 v0, 0, v0, s[18:19]
	v_cvt_pk_fp8_f32 v64, v60, v66 op_sel:[0,0,1]
	v_cvt_pk_fp8_f32 v65, v61, v0 op_sel:[0,0,1]
	v_add_f32_e32 v0, v66, v0
	v_mov_b32_e32 v230, v229
	s_waitcnt vmcnt(19)
	v_mfma_f32_16x16x32_fp8_fp8 v[36:39], v[106:107], v[64:65], v[6:9]
	s_nop 2
	v_add_f32_e32 v6, v56, v57
	v_add_f32_e32 v7, v58, v59
	v_mfma_f32_16x16x32_fp8_fp8 v[40:43], v[108:109], v[64:65], v[10:13]
	v_add_f32_e32 v6, v7, v6
	v_add_f32_e32 v7, v60, v61
	v_add_f32_e32 v6, v7, v6
	s_waitcnt vmcnt(18)
	v_mfma_f32_16x16x32_fp8_fp8 v[44:47], v[110:111], v[64:65], v[14:17]
	v_add_f32_e32 v0, v0, v6
	v_add_f32_e32 v231, v34, v0
	v_mfma_f32_16x16x32_fp8_fp8 v[48:51], v[112:113], v[64:65], v[18:21]
	s_waitcnt vmcnt(17)
	v_mfma_f32_16x16x32_fp8_fp8 v[52:55], v[114:115], v[64:65], v[22:25]
	v_mfma_f32_16x16x32_fp8_fp8 v[56:59], v[116:117], v[64:65], v[26:29]
	s_waitcnt vmcnt(16)
	v_mfma_f32_16x16x32_fp8_fp8 v[60:63], v[134:135], v[64:65], v[30:33]
	v_mfma_f32_16x16x32_fp8_fp8 v[64:67], v[136:137], v[64:65], v[2:5]
	s_nop 1
	s_cmp_gt_i32 s57, s27
	s_mov_b64 s[10:11], -1
	s_cbranch_scc1 .LBB0_892

; #define LAS __attribute__((address_space(3)))
; __device__ __forceinline__ unsigned cvt_pk_bf16(float lo, float hi) { f32x2 v = {lo, hi}; bf16x2_t b = __builtin_convertvector(v, bf16x2_t); return __builtin_bit_cast(unsigned, b); }
; __device__ __forceinline__ float quad_xor1(float v) { return __int_as_float(__builtin_amdgcn_update_dpp(0, __float_as_int(v), 0xB1, 0xF, 0xF, false)); }
; template <int MODE>
; __device__ __forceinline__ void step_fragb(const bf16x8 (&qf)[4], bf16x8 (&kf)[2][4], FragV& cur, const bf16_t* __restrict__ KF, const bf16_t* __restrict__ VF,
;                                            int pos0, int pnext, int lo, int hi, AState& st, int lane, LAS float* imp) {
;     ...
;         for (int T = 0; T < 2; ++T) {
;             float x = 2.f * (p[4 * T] + p[4 * T + 1] + p[4 * T + 2]) + p[4 * T + 3], y = p[4 * T + 3];
;             x += quad_xor1(x); x += quad_xor2(x); y += quad_xor1(y); y += quad_xor2(y);
;             if ((l16 & 3) == 0) { const int a = (pos0 >> 2) + 4 * T + kq; LAS float* ip = imp + (l16 >> 2) * IMP_LD + a;
;                 ip[0] += x;
;                 asm volatile("s_waitcnt lgkmcnt(0)" ::: "memory");
;                 ip[1] += y; }
;             asm volatile("s_waitcnt lgkmcnt(0)" ::: "memory");
;         }
;     } else {
;         if (__builtin_amdgcn_ballot_w64(mx > st.m + 40.f) != 0ull) {
;             mx = fmaxf(mx, __shfl_xor(mx, 16)); mx = fmaxf(mx, __shfl_xor(mx, 32));
;             const float mn = fmaxf(st.m, mx), alpha = __builtin_amdgcn_exp2f(st.m - mn); st.m = mn; st.l *= alpha;
;             if (MODE == 0) {
; #pragma unroll
;                 for (int j = 0; j < 8; ++j) st.o[j] = st.o[j] * alpha;
;             }
;         }
;         float ps = 0.f;
; #pragma unroll
;         for (int j = 0; j < 8; ++j) { p[j] = vd[j] ? __builtin_amdgcn_exp2f(sc[j] - st.m) : 0.f; ps += p[j]; }
;         st.l += ps;
;     }
;     if (MODE != 1) {
;         u32x4 pw; pw.x = cvt_pk_bf16(p[0], p[1]); pw.y = cvt_pk_bf16(p[2], p[3]); pw.z = cvt_pk_bf16(p[4], p[5]); pw.w = cvt_pk_bf16(p[6], p[7]);
;         const bf16x8 pf = __builtin_bit_cast(bf16x8, pw);
; #pragma unroll
;         for (int db = 0; db < 8; ++db) st.o[db] = __builtin_amdgcn_mfma_f32_16x16x32_bf16(cur.v[db], pf, st.o[db], 0, 0, 0);
.LBB0_941:
	s_or_b64 exec, exec, s[10:11]
	v_fma_f32 v114, v114, s79, -v143
	v_fma_f32 v115, v115, s79, -v143
	v_exp_f32_e32 v114, v114
	v_exp_f32_e32 v115, v115
	v_or_b32_e32 v150, 17, v141
	v_or_b32_e32 v151, 16, v140
	v_cmp_lt_i32_e32 vcc, s81, v141
	v_cmp_le_i32_e64 s[12:13], v150, v135
	v_fma_f32 v116, v116, s79, -v143
	v_fma_f32 v117, v117, s79, -v143
	v_cmp_lt_i32_e64 s[10:11], s80, v140
	v_cmp_le_i32_e64 s[14:15], v151, v134
	v_pk_mul_f32 v[150:151], v[138:139], v[114:115]
	s_and_b64 vcc, vcc, s[12:13]
	v_exp_f32_e32 v116, v116
	v_exp_f32_e32 v117, v117
	v_cndmask_b32_e32 v114, 0, v151, vcc
	s_and_b64 vcc, s[10:11], s[14:15]
	v_cndmask_b32_e32 v115, 0, v150, vcc
	v_or_b32_e32 v150, 19, v141
	v_or_b32_e32 v151, 18, v140
	v_cmp_lt_i32_e32 vcc, s83, v141
	v_cmp_le_i32_e64 s[12:13], v150, v135
	v_cmp_lt_i32_e64 s[10:11], s82, v140
	v_cmp_le_i32_e64 s[14:15], v151, v134
	v_pk_mul_f32 v[140:141], v[138:139], v[116:117]
	s_and_b64 vcc, vcc, s[12:13]
	v_cndmask_b32_e32 v116, 0, v141, vcc
	s_and_b64 vcc, s[10:11], s[14:15]
	v_cndmask_b32_e32 v117, 0, v140, vcc
	v_add_f32_e32 v140, v115, v114
	v_add_f32_e32 v140, v117, v140
	v_fma_f32 v140, 2.0, v140, v116
	v_mov_b32_e32 v151, 0
	v_mov_b32_e32 v141, 0
	v_add_f32_dpp v150, v140, v140 quad_perm:[1,0,3,2] row_mask:0xf bank_mask:0xf bound_ctrl:1
	v_add_f32_dpp v140, v116, v116 quad_perm:[1,0,3,2] row_mask:0xf bank_mask:0xf bound_ctrl:1
	s_nop 0
	v_mov_b32_dpp v151, v150 quad_perm:[2,3,0,1] row_mask:0xf bank_mask:0xf
	v_mov_b32_dpp v141, v140 quad_perm:[2,3,0,1] row_mask:0xf bank_mask:0xf
	s_and_saveexec_b64 s[10:11], s[4:5]
	s_cbranch_execz .LBB0_943
	v_add_f32_e32 v150, v150, v151
	v_add_f32_e32 v140, v140, v141
	ds_add_f32 v149, v150 offset:9232
	ds_add_f32 v149, v140 offset:9236
.LBB0_943:
	s_or_b64 exec, exec, s[10:11]
	s_mov_b32 s19, s51
	s_lshl_b64 s[10:11], s[18:19], 13
	v_cvt_pk_bf16_f32 v146, v145, v146
	v_cvt_pk_bf16_f32 v147, v148, v147
	v_cvt_pk_bf16_f32 v148, v115, v114
	v_cvt_pk_bf16_f32 v149, v117, v116
	s_add_u32 s10, s16, s10
	s_addc_u32 s11, s17, s11
	s_waitcnt vmcnt(15)
	v_mfma_f32_16x16x32_bf16 v[46:49], v[86:89], v[146:149], v[46:49]
	s_waitcnt vmcnt(14)
	v_mfma_f32_16x16x32_bf16 v[42:45], v[90:93], v[146:149], v[42:45]
	s_waitcnt vmcnt(13)
	v_mfma_f32_16x16x32_bf16 v[38:41], v[94:97], v[146:149], v[38:41]
	s_waitcnt vmcnt(12)
	v_mfma_f32_16x16x32_bf16 v[34:37], v[98:101], v[146:149], v[34:37]
	s_waitcnt vmcnt(11)
	v_mfma_f32_16x16x32_bf16 v[30:33], v[106:109], v[146:149], v[30:33]
	s_waitcnt vmcnt(10)
	v_mfma_f32_16x16x32_bf16 v[26:29], v[110:113], v[146:149], v[26:29]
	s_waitcnt vmcnt(9)
	v_mfma_f32_16x16x32_bf16 v[18:21], v[102:105], v[146:149], v[18:21]
	s_waitcnt vmcnt(8)
	v_mfma_f32_16x16x32_bf16 v[22:25], v[82:85], v[146:149], v[22:25]
	s_branch .LBB0_945

; template <bool SLC, bool NOMASK> ...
;     ...
;     f32x4 pa, pb; float ps = 0.f;
;     const float mref = st.m - 4.f;
;     if (NOMASK) {
; #pragma unroll
;         for (int j = 0; j < 4; ++j) { pa[j] = __builtin_amdgcn_exp2f(sc[j] - mref); pb[j] = __builtin_amdgcn_exp2f(sc[4 + j] - mref); }
;         if (SLC) {
; #pragma unroll
;             for (int j = 0; j < 4; ++j) { pa[j] = act ? pa[j] : 0.f; pb[j] = act ? pb[j] : 0.f; }
;         }
; #pragma unroll
;         for (int j = 0; j < 4; ++j) ps += pa[j] + pb[j];
;     } else {
; #pragma unroll
;         for (int j = 0; j < 4; ++j) { pa[j] = vd[j] ? __builtin_amdgcn_exp2f(sc[j] - mref) : 0.f; pb[j] = vd[4 + j] ? __builtin_amdgcn_exp2f(sc[4 + j] - mref) : 0.f; ps += pa[j] + pb[j]; }
;     }
;     st.l += ps;
;     const u32x2 pw = pack8_fp8(pa, pb);
;     const i64_t pf = __builtin_bit_cast(i64_t, pw);
; #pragma unroll
;     for (int db = 0; db < 8; ++db) st.o[db] = __builtin_amdgcn_mfma_f32_16x16x32_fp8_fp8(cur.v[db], pf, st.o[db], 0, 0, 0);
.LBB0_971:
	v_add_f32_e32 v34, -4.0, v0
	v_sub_f32_e32 v2, v2, v34
	v_sub_f32_e32 v6, v6, v34
	v_sub_f32_e32 v3, v3, v34
	v_sub_f32_e32 v7, v7, v34
	v_exp_f32_e32 v2, v2
	v_exp_f32_e32 v6, v6
	v_exp_f32_e32 v3, v3
	v_exp_f32_e32 v7, v7
	v_sub_f32_e32 v4, v4, v34
	v_sub_f32_e32 v8, v8, v34
	v_sub_f32_e32 v5, v5, v34
	v_sub_f32_e32 v9, v9, v34
	v_exp_f32_e32 v4, v4
	v_exp_f32_e32 v8, v8
	v_exp_f32_e32 v5, v5
	v_exp_f32_e32 v9, v9
	v_cndmask_b32_e64 v34, 0, v2, s[10:11]
	v_cndmask_b32_e64 v6, 0, v6, s[10:11]
	v_cndmask_b32_e64 v35, 0, v3, s[10:11]
	v_cndmask_b32_e64 v7, 0, v7, s[10:11]
	v_mov_b32_e32 v2, v1
	v_mov_b32_e32 v3, v1
	v_cvt_pk_fp8_f32 v2, v34, v35
	v_cvt_pk_fp8_f32 v3, v6, v7
	v_cndmask_b32_e64 v4, 0, v4, s[10:11]
	v_cndmask_b32_e64 v205, 0, v8, s[10:11]
	v_cndmask_b32_e64 v5, 0, v5, s[10:11]
	v_cndmask_b32_e64 v227, 0, v9, s[10:11]
	v_add_f32_e32 v6, v34, v6
	v_cvt_pk_fp8_f32 v2, v4, v5 op_sel:[0,0,1]
	v_cvt_pk_fp8_f32 v3, v205, v227 op_sel:[0,0,1]
	v_add_f32_e32 v7, v35, v7
	v_add_f32_e32 v6, v7, v6
	v_add_f32_e32 v4, v4, v205
	v_add_f32_e32 v4, v4, v6
	v_add_f32_e32 v5, v5, v227
	v_add_f32_e32 v4, v5, v4
	s_waitcnt vmcnt(19)
	v_mfma_f32_16x16x32_fp8_fp8 v[8:11], v[90:91], v[2:3], v[64:67]
	v_add_f32_e32 v133, v133, v4
	v_mfma_f32_16x16x32_fp8_fp8 v[12:15], v[92:93], v[2:3], v[60:63]
	s_waitcnt vmcnt(18)
	v_mfma_f32_16x16x32_fp8_fp8 v[16:19], v[94:95], v[2:3], v[56:59]
	v_mfma_f32_16x16x32_fp8_fp8 v[20:23], v[96:97], v[2:3], v[52:55]
	s_waitcnt vmcnt(17)
	v_mfma_f32_16x16x32_fp8_fp8 v[24:27], v[98:99], v[2:3], v[48:51]
	v_mfma_f32_16x16x32_fp8_fp8 v[32:35], v[100:101], v[2:3], v[44:47]
	s_waitcnt vmcnt(16)
	v_mfma_f32_16x16x32_fp8_fp8 v[28:31], v[102:103], v[2:3], v[40:43]
	v_mfma_f32_16x16x32_fp8_fp8 v[4:7], v[104:105], v[2:3], v[36:39]
	s_nop 1
	s_branch .LBB0_965

; template <bool SLC, bool NOMASK> ...
;     ...
;     } else {
; #pragma unroll
;         for (int j = 0; j < 4; ++j) { pa[j] = vd[j] ? __builtin_amdgcn_exp2f(sc[j] - mref) : 0.f; pb[j] = vd[4 + j] ? __builtin_amdgcn_exp2f(sc[4 + j] - mref) : 0.f; ps += pa[j] + pb[j]; }
;     }
;     st.l += ps;
;     const u32x2 pw = pack8_fp8(pa, pb);
;     const i64_t pf = __builtin_bit_cast(i64_t, pw);
; #pragma unroll
;     for (int db = 0; db < 8; ++db) st.o[db] = __builtin_amdgcn_mfma_f32_16x16x32_fp8_fp8(cur.v[db], pf, st.o[db], 0, 0, 0);
.LBB0_974:
	v_add_f32_e32 v0, -4.0, v202
	v_sub_f32_e32 v2, v2, v0
	v_exp_f32_e32 v2, v2
	v_sub_f32_e32 v6, v6, v0
	v_exp_f32_e32 v6, v6
	v_sub_f32_e32 v4, v4, v0
	v_cndmask_b32_e64 v28, 0, v2, s[16:17]
	v_sub_f32_e32 v2, v3, v0
	v_exp_f32_e32 v2, v2
	v_sub_f32_e32 v3, v7, v0
	v_exp_f32_e32 v3, v3
	v_sub_f32_e32 v7, v8, v0
	v_cndmask_b32_e64 v29, 0, v2, s[12:13]
	v_sub_f32_e32 v2, v5, v0
	v_sub_f32_e32 v0, v9, v0
	v_cndmask_b32_e64 v6, 0, v6, s[24:25]
	v_exp_f32_e32 v4, v4
	v_exp_f32_e32 v7, v7
	v_cndmask_b32_e64 v30, 0, v3, s[20:21]
	v_exp_f32_e32 v5, v2
	v_exp_f32_e32 v0, v0
	v_mov_b32_e32 v2, v1
	v_mov_b32_e32 v3, v1
	v_cvt_pk_fp8_f32 v2, v28, v29
	v_cvt_pk_fp8_f32 v3, v6, v30
	v_cndmask_b32_e64 v4, 0, v4, s[14:15]
	v_cndmask_b32_e64 v7, 0, v7, s[22:23]
	v_cndmask_b32_e64 v5, 0, v5, s[10:11]
	v_cndmask_b32_e64 v0, 0, v0, s[18:19]
	v_cvt_pk_fp8_f32 v2, v4, v5 op_sel:[0,0,1]
	v_cvt_pk_fp8_f32 v3, v7, v0 op_sel:[0,0,1]
	v_add_f32_e32 v6, v28, v6
	v_add_f32_e32 v28, v29, v30
	v_add_f32_e32 v6, v28, v6
	v_add_f32_e32 v4, v4, v7
	v_add_f32_e32 v4, v4, v6
	v_add_f32_e32 v0, v5, v0
	s_waitcnt vmcnt(19)
	v_mfma_f32_16x16x32_fp8_fp8 v[8:11], v[90:91], v[2:3], v[64:67]
	v_add_f32_e32 v0, v0, v4
	v_add_f32_e32 v133, v203, v0
	v_mov_b32_e32 v0, v202
	v_mfma_f32_16x16x32_fp8_fp8 v[12:15], v[92:93], v[2:3], v[60:63]
	s_waitcnt vmcnt(18)
	v_mfma_f32_16x16x32_fp8_fp8 v[16:19], v[94:95], v[2:3], v[56:59]
	v_mfma_f32_16x16x32_fp8_fp8 v[20:23], v[96:97], v[2:3], v[52:55]
	s_waitcnt vmcnt(17)
	v_mfma_f32_16x16x32_fp8_fp8 v[24:27], v[98:99], v[2:3], v[48:51]
	v_mfma_f32_16x16x32_fp8_fp8 v[32:35], v[100:101], v[2:3], v[44:47]
	s_waitcnt vmcnt(16)
	v_mfma_f32_16x16x32_fp8_fp8 v[28:31], v[102:103], v[2:3], v[40:43]
	v_mfma_f32_16x16x32_fp8_fp8 v[4:7], v[104:105], v[2:3], v[36:39]
	s_nop 1
	s_add_i32 s10, s56, -3
	s_cmp_ge_u32 s10, s54
	s_mov_b64 s[10:11], -1
	s_cbranch_scc0 .LBB0_966

; template <bool SLC, bool NOMASK> ...
;     ...
;     f32x4 pa, pb; float ps = 0.f;
;     const float mref = st.m - 4.f;
;     if (NOMASK) {
; #pragma unroll
;         for (int j = 0; j < 4; ++j) { pa[j] = __builtin_amdgcn_exp2f(sc[j] - mref); pb[j] = __builtin_amdgcn_exp2f(sc[4 + j] - mref); }
;         if (SLC) {
; #pragma unroll
;             for (int j = 0; j < 4; ++j) { pa[j] = act ? pa[j] : 0.f; pb[j] = act ? pb[j] : 0.f; }
;         }
; #pragma unroll
;         for (int j = 0; j < 4; ++j) ps += pa[j] + pb[j];
;     } else {
; #pragma unroll
;         for (int j = 0; j < 4; ++j) { pa[j] = vd[j] ? __builtin_amdgcn_exp2f(sc[j] - mref) : 0.f; pb[j] = vd[4 + j] ? __builtin_amdgcn_exp2f(sc[4 + j] - mref) : 0.f; ps += pa[j] + pb[j]; }
;     }
;     st.l += ps;
;     const u32x2 pw = pack8_fp8(pa, pb);
;     const i64_t pf = __builtin_bit_cast(i64_t, pw);
; #pragma unroll
;     for (int db = 0; db < 8; ++db) st.o[db] = __builtin_amdgcn_mfma_f32_16x16x32_fp8_fp8(cur.v[db], pf, st.o[db], 0, 0, 0);
.LBB0_985:
	v_add_f32_e32 v34, -4.0, v202
	v_sub_f32_e32 v2, v2, v34
	v_sub_f32_e32 v6, v6, v34
	v_sub_f32_e32 v3, v3, v34
	v_sub_f32_e32 v7, v7, v34
	v_exp_f32_e32 v2, v2
	v_exp_f32_e32 v6, v6
	v_exp_f32_e32 v3, v3
	v_exp_f32_e32 v7, v7
	v_sub_f32_e32 v4, v4, v34
	v_sub_f32_e32 v8, v8, v34
	v_sub_f32_e32 v5, v5, v34
	v_sub_f32_e32 v9, v9, v34
	v_exp_f32_e32 v4, v4
	v_exp_f32_e32 v8, v8
	v_exp_f32_e32 v5, v5
	v_exp_f32_e32 v9, v9
	v_cndmask_b32_e64 v34, 0, v2, s[10:11]
	v_cndmask_b32_e64 v6, 0, v6, s[10:11]
	v_cndmask_b32_e64 v35, 0, v3, s[10:11]
	v_cndmask_b32_e64 v7, 0, v7, s[10:11]
	v_mov_b32_e32 v2, v1
	v_mov_b32_e32 v3, v1
	v_cvt_pk_fp8_f32 v2, v34, v35
	v_cvt_pk_fp8_f32 v3, v6, v7
	v_cndmask_b32_e64 v4, 0, v4, s[10:11]
	v_cndmask_b32_e64 v205, 0, v8, s[10:11]
	v_cndmask_b32_e64 v5, 0, v5, s[10:11]
	v_cndmask_b32_e64 v227, 0, v9, s[10:11]
	v_add_f32_e32 v6, v34, v6
	v_cvt_pk_fp8_f32 v2, v4, v5 op_sel:[0,0,1]
	v_cvt_pk_fp8_f32 v3, v205, v227 op_sel:[0,0,1]
	v_add_f32_e32 v7, v35, v7
	v_add_f32_e32 v6, v7, v6
	v_add_f32_e32 v4, v4, v205
	v_add_f32_e32 v4, v4, v6
	v_add_f32_e32 v5, v5, v227
	v_add_f32_e32 v4, v5, v4
	s_waitcnt vmcnt(19)
	v_mfma_f32_16x16x32_fp8_fp8 v[8:11], v[170:171], v[2:3], v[36:39]
	v_add_f32_e32 v133, v133, v4
	s_mov_b64 s[10:11], 0
	v_mfma_f32_16x16x32_fp8_fp8 v[12:15], v[172:173], v[2:3], v[40:43]
	s_waitcnt vmcnt(18)
	v_mfma_f32_16x16x32_fp8_fp8 v[16:19], v[174:175], v[2:3], v[44:47]
	v_mfma_f32_16x16x32_fp8_fp8 v[20:23], v[176:177], v[2:3], v[48:51]
	s_waitcnt vmcnt(17)
	v_mfma_f32_16x16x32_fp8_fp8 v[24:27], v[178:179], v[2:3], v[52:55]
	v_mfma_f32_16x16x32_fp8_fp8 v[32:35], v[180:181], v[2:3], v[56:59]
	s_waitcnt vmcnt(16)
	v_mfma_f32_16x16x32_fp8_fp8 v[28:31], v[182:183], v[2:3], v[60:63]
	v_mfma_f32_16x16x32_fp8_fp8 v[4:7], v[184:185], v[2:3], v[64:67]
	s_nop 1

; template <bool SLC, bool NOMASK> ...
;     ...
;     } else {
; #pragma unroll
;         for (int j = 0; j < 4; ++j) { pa[j] = vd[j] ? __builtin_amdgcn_exp2f(sc[j] - mref) : 0.f; pb[j] = vd[4 + j] ? __builtin_amdgcn_exp2f(sc[4 + j] - mref) : 0.f; ps += pa[j] + pb[j]; }
;     }
;     st.l += ps;
;     const u32x2 pw = pack8_fp8(pa, pb);
;     const i64_t pf = __builtin_bit_cast(i64_t, pw);
; #pragma unroll
;     for (int db = 0; db < 8; ++db) st.o[db] = __builtin_amdgcn_mfma_f32_16x16x32_fp8_fp8(cur.v[db], pf, st.o[db], 0, 0, 0);
.LBB0_1014:
	v_add_f32_e32 v0, -4.0, v228
	v_sub_f32_e32 v36, v36, v0
	v_exp_f32_e32 v36, v36
	v_sub_f32_e32 v40, v40, v0
	v_exp_f32_e32 v40, v40
	v_sub_f32_e32 v38, v38, v0
	v_cndmask_b32_e64 v56, 0, v36, s[16:17]
	v_sub_f32_e32 v36, v37, v0
	v_exp_f32_e32 v36, v36
	v_sub_f32_e32 v37, v41, v0
	v_exp_f32_e32 v37, v37
	v_cndmask_b32_e64 v57, 0, v40, s[24:25]
	v_sub_f32_e32 v40, v42, v0
	v_cndmask_b32_e64 v58, 0, v36, s[12:13]
	v_sub_f32_e32 v36, v39, v0
	v_sub_f32_e32 v0, v43, v0
	v_exp_f32_e32 v38, v38
	v_exp_f32_e32 v40, v40
	v_cndmask_b32_e64 v59, 0, v37, s[20:21]
	v_exp_f32_e32 v36, v36
	v_exp_f32_e32 v0, v0
	v_mov_b32_e32 v64, v1
	v_mov_b32_e32 v65, v1
	v_cvt_pk_fp8_f32 v64, v56, v58
	v_cvt_pk_fp8_f32 v65, v57, v59
	v_cndmask_b32_e64 v60, 0, v38, s[14:15]
	v_cndmask_b32_e64 v61, 0, v40, s[22:23]
	v_cndmask_b32_e64 v66, 0, v36, s[10:11]
	v_cndmask_b32_e64 v0, 0, v0, s[18:19]
	v_cvt_pk_fp8_f32 v64, v60, v66 op_sel:[0,0,1]
	v_cvt_pk_fp8_f32 v65, v61, v0 op_sel:[0,0,1]
	v_add_f32_e32 v0, v66, v0
	v_mov_b32_e32 v227, v228
	s_waitcnt vmcnt(19)
	v_mfma_f32_16x16x32_fp8_fp8 v[36:39], v[106:107], v[64:65], v[6:9]
	s_nop 2
	v_add_f32_e32 v6, v56, v57
	v_add_f32_e32 v7, v58, v59
	v_mfma_f32_16x16x32_fp8_fp8 v[40:43], v[108:109], v[64:65], v[10:13]
	v_add_f32_e32 v6, v7, v6
	v_add_f32_e32 v7, v60, v61
	v_add_f32_e32 v6, v7, v6
	s_waitcnt vmcnt(18)
	v_mfma_f32_16x16x32_fp8_fp8 v[44:47], v[110:111], v[64:65], v[14:17]
	v_add_f32_e32 v0, v0, v6
	v_add_f32_e32 v229, v34, v0
	v_mfma_f32_16x16x32_fp8_fp8 v[48:51], v[112:113], v[64:65], v[18:21]
	s_waitcnt vmcnt(17)
	v_mfma_f32_16x16x32_fp8_fp8 v[52:55], v[114:115], v[64:65], v[22:25]
	v_mfma_f32_16x16x32_fp8_fp8 v[56:59], v[116:117], v[64:65], v[26:29]
	s_waitcnt vmcnt(16)
	v_mfma_f32_16x16x32_fp8_fp8 v[60:63], v[134:135], v[64:65], v[30:33]
	v_mfma_f32_16x16x32_fp8_fp8 v[64:67], v[136:137], v[64:65], v[2:5]
	s_nop 1
	s_cmp_gt_i32 s55, s27
	s_mov_b64 s[10:11], -1
	s_cbranch_scc1 .LBB0_994
